# speedup vs baseline: 1.0504x; 1.0030x over previous
; __device__ __forceinline__ float fast_exp2(float x) { return __builtin_amdgcn_exp2f(x); }
; __device__ __forceinline__ void df_block(const Params& P, int l, int b, int qrow_blk, int h, int tk_lo, int tk_hi, char* smem) {
;     ...
;   for (int tk = tk_lo; tk < tk_hi; tk += 64) {
;     const int tn = (tk + 64 < tk_hi) ? tk + 64 : tk;
;     rk0 = *(const uint4*)(KD + (size_t)key_row(b, tn + lrow0) * 384 + h * 64 + lch * 8);
;     rk1 = *(const uint4*)(KD + (size_t)key_row(b, tn + lrow0 + 32) * 384 + h * 64 + lch * 8);
;     rv0 = *(const uint4*)(vsrc0 + tn);
;     rv1 = *(const uint4*)(vsrc1 + tn);
;     __builtin_amdgcn_sched_barrier(0);
;     const char* Ks = smem + cur * DF_BUF;
;     const char* Vs = Ks + DF_KBYTES;
; #pragma unroll
;     for (int sub = 0; sub < 2; ++sub) {
;       const char* kp = Ks + (sub * 32 + ql) * DF_KSTR + hh * 16;
;       bf16x8 pa0, pa1, pb0, pb1;
;       {
;         f32x16 S = mfma32(*(const bf16x8*)(kp), q1[0], cini);
;         S = mfma32(*(const bf16x8*)(kp + 32), q1[1], S);
;         float p[16];
; #pragma unroll
;         for (int j = 0; j < 16; ++j) { p[j] = fast_exp2(S[j]); l1 += p[j]; }
;         pack_p(p, pa0, pa1);
;       }
;       {
;         f32x16 S = mfma32(*(const bf16x8*)(kp + 64), q2[0], cini);
;         S = mfma32(*(const bf16x8*)(kp + 96), q2[1], S);
;         float p[16];
; #pragma unroll
;         for (int j = 0; j < 16; ++j) { p[j] = fast_exp2(S[j]); l2 += p[j]; }
;         pack_p(p, pb0, pb1);
;       }
; #pragma unroll
;       for (int s2 = 0; s2 < 2; ++s2) {
;         const char* vp0 = Vs + ql * DF_VSTR + (sub * 32 + 16 * s2 + 4 * hh) * 2;
;         const char* vp1 = vp0 + 32 * DF_VSTR;
;         union { uint4 u; bf16x8 v; } c0, c1;
;         uint2 a0 = *(const uint2*)(vp0), a1 = *(const uint2*)(vp0 + 16);
;         uint2 e0 = *(const uint2*)(vp1), e1 = *(const uint2*)(vp1 + 16);
;         c0.u = make_uint4(a0.x, a0.y, a1.x, a1.y);
;         c1.u = make_uint4(e0.x, e0.y, e1.x, e1.y);
;         o1[0] = mfma32(c0.v, s2 ? pa1 : pa0, o1[0]);
;         o1[1] = mfma32(c1.v, s2 ? pa1 : pa0, o1[1]);
;         o2[0] = mfma32(c0.v, s2 ? pb1 : pb0, o2[0]);
;         o2[1] = mfma32(c1.v, s2 ? pb1 : pb0, o2[1]);
;       }
;     }
.LBB0_405:
	s_add_i32 s15, s17, 64
	s_cmpk_lt_u32 s17, 0x10c0
	s_cselect_b64 s[0:1], -1, 0
	s_and_b64 vcc, s[0:1], exec
	s_cselect_b32 s10, s15, s17
	v_add_u32_e32 v86, s10, v137
	v_cmp_gt_u32_e64 s[0:1], s31, v86
	s_lshl_b64 s[18:19], s[10:11], 1
	v_lshl_add_u64 v[82:83], v[170:171], 0, s[18:19]
	v_cndmask_b32_e64 v87, v235, v165, s[0:1]
	v_cmp_gt_u32_e64 s[0:1], s34, v86
	v_add_u32_e32 v87, v87, v86
	v_lshl_add_u64 v[84:85], v[172:173], 0, s[18:19]
	v_cndmask_b32_e64 v88, v163, v138, s[0:1]
	v_add_u32_e32 v86, v88, v86
	global_load_dwordx4 v[118:121], v[82:83], off
	global_load_dwordx4 v[114:117], v[84:85], off
	v_mad_i64_i32 v[82:83], s[0:1], v87, s29, v[174:175]
	v_mad_i64_i32 v[84:85], s[0:1], v86, s29, v[174:175]
	global_load_dwordx4 v[122:125], v[82:83], off
	global_load_dwordx4 v[126:129], v[84:85], off
	s_mul_i32 s0, s14, 0x4600
	s_xor_b32 s14, s14, 1
	v_or_b32_e32 v82, s0, v140
	v_add3_u32 v218, s0, v223, v136
	s_mul_i32 s0, s14, 0x4600
	v_add_u32_e32 v236, s0, v141
	v_add_u32_e32 v219, v82, v224
	v_add_u32_e32 v237, s0, v143
	v_add_u32_e32 v238, 0x2400, v236
	ds_read_b128 v[176:179], v219
	ds_read_b128 v[180:183], v219 offset:32
	ds_read_b128 v[196:199], v219 offset:64
	v_add_u32_e32 v239, 0x2000, v218
	v_add_u32_e32 v248, 0x3000, v218
	s_waitcnt lgkmcnt(2)
	v_mfma_f32_32x32x16_bf16 v[82:97], v[176:179], v[98:101], v[50:65]
	s_waitcnt lgkmcnt(1)
	v_mfma_f32_32x32x16_bf16 v[82:97], v[180:183], v[102:105], v[82:97]
	s_nop 11
	v_exp_f32_e32 v132, v82
	v_exp_f32_e32 v200, v83
	v_exp_f32_e32 v202, v84
	v_exp_f32_e32 v204, v85
	v_exp_f32_e32 v206, v86
	v_exp_f32_e32 v208, v87
	v_exp_f32_e32 v210, v88
	v_exp_f32_e32 v212, v89
	v_exp_f32_e32 v214, v90
	v_exp_f32_e32 v216, v91
	v_exp_f32_e32 v186, v92
	v_exp_f32_e32 v184, v93
	v_exp_f32_e32 v182, v94
	v_exp_f32_e32 v180, v95
	v_exp_f32_e32 v178, v96
	v_exp_f32_e32 v176, v97
	s_waitcnt lgkmcnt(0)
	v_mfma_f32_32x32x16_bf16 v[82:97], v[196:199], v[106:109], v[50:65]
	ds_read_b128 v[196:199], v219 offset:96
	v_cvt_pk_bf16_f32 v188, v132, v200
	v_cvt_pk_bf16_f32 v189, v202, v204
	v_cvt_pk_bf16_f32 v190, v206, v208
	v_cvt_pk_bf16_f32 v191, v210, v212
	v_cvt_pk_bf16_f32 v192, v214, v216
	v_cvt_pk_bf16_f32 v193, v186, v184
	s_waitcnt lgkmcnt(0)
	v_mfma_f32_32x32x16_bf16 v[82:97], v[196:199], v[110:113], v[82:97]
	v_cvt_pk_bf16_f32 v194, v182, v180
	v_cvt_pk_bf16_f32 v195, v178, v176
	s_nop 11
	v_exp_f32_e32 v215, v90
	v_exp_f32_e32 v217, v91
	v_exp_f32_e32 v187, v92
	v_exp_f32_e32 v185, v93
	v_exp_f32_e32 v183, v94
	v_exp_f32_e32 v181, v95
	v_exp_f32_e32 v179, v96
	v_exp_f32_e32 v177, v97
	ds_read2_b64 v[90:93], v239 offset0:128 offset1:130
	ds_read2_b64 v[94:97], v239 offset0:132 offset1:134
	ds_read2_b64 v[196:199], v248 offset0:160 offset1:162
	v_exp_f32_e32 v133, v82
	v_exp_f32_e32 v201, v83
	v_exp_f32_e32 v203, v84
	v_exp_f32_e32 v205, v85
	v_exp_f32_e32 v207, v86
	v_exp_f32_e32 v209, v87
	v_exp_f32_e32 v211, v88
	v_exp_f32_e32 v213, v89
	v_cvt_pk_bf16_f32 v82, v133, v201
	v_cvt_pk_bf16_f32 v83, v203, v205
	v_cvt_pk_bf16_f32 v84, v207, v209
	v_cvt_pk_bf16_f32 v85, v211, v213
	s_waitcnt lgkmcnt(0)
	v_mfma_f32_32x32x16_bf16 v[2:17], v[196:199], v[188:191], v[2:17]
	v_cvt_pk_bf16_f32 v86, v215, v217
	v_cvt_pk_bf16_f32 v87, v187, v185
	v_cvt_pk_bf16_f32 v88, v183, v181
	v_cvt_pk_bf16_f32 v89, v179, v177
	ds_read_b128 v[244:247], v219 offset:4672
	v_mfma_f32_32x32x16_bf16 v[66:81], v[90:93], v[82:85], v[66:81]
	v_mfma_f32_32x32x16_bf16 v[18:33], v[196:199], v[82:85], v[18:33]
	ds_read2_b64 v[82:85], v248 offset0:164 offset1:166
	s_waitcnt lgkmcnt(0)
	v_mfma_f32_32x32x16_bf16 v[2:17], v[82:85], v[192:195], v[2:17]
	v_mfma_f32_32x32x16_bf16 v[18:33], v[82:85], v[86:89], v[18:33]
	v_add_f32_e64 v82, v130, v132
	v_add_f32_e64 v83, v131, v133
	ds_read_b128 v[130:133], v219 offset:4608
	v_add_f32_e64 v82, v200, v82
	v_add_f32_e64 v83, v201, v83
	v_add_f32_e32 v82, v202, v82
	v_add_f32_e32 v83, v203, v83
	s_nop 0
	v_add_f32_e32 v82, v204, v82
	v_add_f32_e32 v83, v205, v83
	v_mfma_f32_32x32x16_bf16 v[34:49], v[90:93], v[188:191], v[34:49]
	v_add_f32_e64 v82, v206, v82
	v_add_f32_e64 v83, v207, v83
	v_add_f32_e64 v82, v208, v82
	v_add_f32_e64 v83, v209, v83
	v_add_f32_e64 v82, v210, v82
	v_add_f32_e64 v83, v211, v83
	v_add_f32_e32 v82, v212, v82
	v_add_f32_e32 v83, v213, v83
	v_mfma_f32_32x32x16_bf16 v[34:49], v[94:97], v[192:195], v[34:49]
	v_add_f32_e64 v82, v214, v82
	v_add_f32_e64 v83, v215, v83
	v_add_f32_e64 v188, v216, v82
	v_add_f32_e64 v189, v217, v83
	v_mfma_f32_32x32x16_bf16 v[66:81], v[94:97], v[86:89], v[66:81]
	s_waitcnt lgkmcnt(0)
	v_mfma_f32_32x32x16_bf16 v[82:97], v[130:133], v[98:101], v[50:65]
	ds_read_b128 v[130:133], v219 offset:4640
	s_waitcnt lgkmcnt(0)
	v_mfma_f32_32x32x16_bf16 v[82:97], v[130:133], v[102:105], v[82:97]
	s_nop 11
	v_exp_f32_e32 v220, v82
	v_exp_f32_e32 v218, v83
	v_exp_f32_e32 v216, v84
	v_exp_f32_e32 v214, v85
	v_exp_f32_e32 v212, v86
	v_exp_f32_e32 v210, v87
	v_exp_f32_e32 v208, v88
	v_exp_f32_e32 v206, v89
	v_exp_f32_e32 v204, v90
	v_exp_f32_e32 v202, v91
	v_exp_f32_e32 v200, v92
	v_exp_f32_e32 v198, v93
	v_exp_f32_e32 v196, v94
	v_exp_f32_e32 v194, v95
	v_exp_f32_e32 v192, v96
	v_exp_f32_e32 v190, v97
	v_mfma_f32_32x32x16_bf16 v[82:97], v[244:247], v[106:109], v[50:65]
	ds_read_b128 v[244:247], v219 offset:4704
	v_cvt_pk_bf16_f32 v240, v220, v218
	v_cvt_pk_bf16_f32 v241, v216, v214
	v_cvt_pk_bf16_f32 v242, v212, v210
	v_cvt_pk_bf16_f32 v243, v208, v206
	v_cvt_pk_bf16_f32 v130, v204, v202
	v_cvt_pk_bf16_f32 v131, v200, v198
	s_waitcnt lgkmcnt(0)
; __device__ __forceinline__ float fast_exp2(float x) { return __builtin_amdgcn_exp2f(x); }
; __device__ __forceinline__ void df_block(const Params& P, int l, int b, int qrow_blk, int h, int tk_lo, int tk_hi, char* smem) {
;     ...
;         for (int j = 0; j < 16; ++j) { p[j] = fast_exp2(S[j]); l1 += p[j]; }
;         pack_p(p, pa0, pa1);
;       }
;       {
;         f32x16 S = mfma32(*(const bf16x8*)(kp + 64), q2[0], cini);
;         S = mfma32(*(const bf16x8*)(kp + 96), q2[1], S);
;         float p[16];
; #pragma unroll
;         for (int j = 0; j < 16; ++j) { p[j] = fast_exp2(S[j]); l2 += p[j]; }
;         pack_p(p, pb0, pb1);
;       }
; #pragma unroll
;       for (int s2 = 0; s2 < 2; ++s2) {
;         const char* vp0 = Vs + ql * DF_VSTR + (sub * 32 + 16 * s2 + 4 * hh) * 2;
;         const char* vp1 = vp0 + 32 * DF_VSTR;
;         union { uint4 u; bf16x8 v; } c0, c1;
;         uint2 a0 = *(const uint2*)(vp0), a1 = *(const uint2*)(vp0 + 16);
;         uint2 e0 = *(const uint2*)(vp1), e1 = *(const uint2*)(vp1 + 16);
;         c0.u = make_uint4(a0.x, a0.y, a1.x, a1.y);
;         c1.u = make_uint4(e0.x, e0.y, e1.x, e1.y);
;         o1[0] = mfma32(c0.v, s2 ? pa1 : pa0, o1[0]);
;         o1[1] = mfma32(c1.v, s2 ? pa1 : pa0, o1[1]);
;         o2[0] = mfma32(c0.v, s2 ? pb1 : pb0, o2[0]);
;         o2[1] = mfma32(c1.v, s2 ? pb1 : pb0, o2[1]);
;       }
;     }
;     __builtin_amdgcn_sched_barrier(0);
;     {
;       char* d = smem + (cur ^ 1) * DF_BUF;
;       *(uint4*)(d + koff0) = rk0;
;       *(uint4*)(d + koff1) = rk1;
;       *(uint2*)(d + voff0) = make_uint2(rv0.x, rv0.y); *(uint2*)(d + voff0 + 8) = make_uint2(rv0.z, rv0.w);
;       *(uint2*)(d + voff1) = make_uint2(rv1.x, rv1.y); *(uint2*)(d + voff1 + 8) = make_uint2(rv1.z, rv1.w);
;     }
;     __syncthreads();
;     cur ^= 1;
;   }
;   l1 += __shfl_xor(l1, 32);
;   l2 += __shfl_xor(l2, 32);
;   const float r1 = 1.f / l1, r2 = lam / l2;
;   float ss = 0.f;
; #pragma unroll
;   for (int m = 0; m < 2; ++m)
; #pragma unroll
;     for (int j = 0; j < 16; ++j) {
;       float v = o1[m][j] * r1 - o2[m][j] * r2;
;       o1[m][j] = v;
;       ss += v * v;
;     }
;   ss += __shfl_xor(ss, 32);
;   const float rinv = rsqrtf(ss * (1.f / 64.f) + EPS) * (1.f - lam_init);
	v_mfma_f32_32x32x16_bf16 v[82:97], v[244:247], v[110:113], v[82:97]
	v_cvt_pk_bf16_f32 v132, v196, v194
	v_cvt_pk_bf16_f32 v133, v192, v190
	s_nop 11
	v_exp_f32_e32 v205, v90
	v_exp_f32_e32 v203, v91
	v_exp_f32_e32 v201, v92
	v_exp_f32_e32 v199, v93
	v_exp_f32_e32 v197, v94
	v_exp_f32_e32 v195, v95
	v_exp_f32_e32 v193, v96
	v_exp_f32_e32 v191, v97
	ds_read2_b64 v[90:93], v239 offset0:136 offset1:138
	ds_read2_b64 v[94:97], v248 offset0:168 offset1:170
	v_exp_f32_e32 v221, v82
	v_exp_f32_e32 v219, v83
	v_exp_f32_e32 v217, v84
	v_exp_f32_e32 v215, v85
	v_exp_f32_e32 v213, v86
	v_exp_f32_e32 v211, v87
	v_exp_f32_e32 v209, v88
	v_exp_f32_e32 v207, v89
	v_cvt_pk_bf16_f32 v86, v221, v219
	v_cvt_pk_bf16_f32 v87, v217, v215
	v_cvt_pk_bf16_f32 v88, v213, v211
	v_cvt_pk_bf16_f32 v89, v209, v207
	s_waitcnt lgkmcnt(1)
	v_mfma_f32_32x32x16_bf16 v[34:49], v[90:93], v[240:243], v[34:49]
	v_cvt_pk_bf16_f32 v82, v205, v203
	v_cvt_pk_bf16_f32 v83, v201, v199
	v_cvt_pk_bf16_f32 v84, v197, v195
	v_cvt_pk_bf16_f32 v85, v193, v191
	v_mfma_f32_32x32x16_bf16 v[66:81], v[90:93], v[86:89], v[66:81]
	s_waitcnt lgkmcnt(0)
	v_mfma_f32_32x32x16_bf16 v[18:33], v[94:97], v[86:89], v[18:33]
	ds_read2_b64 v[86:89], v239 offset0:140 offset1:142
	ds_read2_b64 v[90:93], v248 offset0:172 offset1:174
	s_waitcnt lgkmcnt(1)
	v_mfma_f32_32x32x16_bf16 v[66:81], v[86:89], v[82:85], v[66:81]
	s_waitcnt lgkmcnt(0)
	v_mfma_f32_32x32x16_bf16 v[18:33], v[90:93], v[82:85], v[18:33]
	v_add_f32_e64 v82, v186, v188
	v_add_f32_e64 v83, v187, v189
	v_add_f32_e64 v82, v184, v82
	v_add_f32_e64 v83, v185, v83
	v_add_f32_e64 v82, v182, v82
	v_add_f32_e64 v83, v183, v83
	v_add_f32_e32 v82, v180, v82
	v_add_f32_e32 v83, v181, v83
	v_mfma_f32_32x32x16_bf16 v[2:17], v[94:97], v[240:243], v[2:17]
	v_add_f32_e64 v82, v178, v82
	v_add_f32_e64 v83, v179, v83
	v_add_f32_e64 v82, v176, v82
	v_add_f32_e64 v83, v177, v83
	v_add_f32_e64 v82, v82, v220
	v_add_f32_e64 v83, v83, v221
	v_add_f32_e32 v82, v218, v82
	v_add_f32_e32 v83, v219, v83
	v_mfma_f32_32x32x16_bf16 v[34:49], v[86:89], v[130:133], v[34:49]
	v_add_f32_e64 v82, v216, v82
	v_add_f32_e64 v83, v217, v83
	v_add_f32_e64 v82, v214, v82
	v_add_f32_e64 v83, v215, v83
	v_add_f32_e64 v82, v212, v82
	v_add_f32_e64 v83, v213, v83
	v_add_f32_e32 v82, v210, v82
	v_add_f32_e32 v83, v211, v83
	v_mfma_f32_32x32x16_bf16 v[2:17], v[90:93], v[130:133], v[2:17]
	v_add_f32_e64 v82, v208, v82
	v_add_f32_e64 v83, v209, v83
	v_add_f32_e64 v82, v206, v82
	v_add_f32_e64 v83, v207, v83
	v_add_f32_e64 v82, v204, v82
	v_add_f32_e64 v83, v205, v83
	v_add_f32_e32 v82, v202, v82
	v_add_f32_e32 v83, v203, v83
	s_nop 0
	v_add_f32_e32 v82, v200, v82
	v_add_f32_e32 v83, v201, v83
	s_nop 0
	v_add_f32_e32 v82, v198, v82
	v_add_f32_e32 v83, v199, v83
	s_nop 0
	v_add_f32_e32 v82, v196, v82
	v_add_f32_e32 v83, v197, v83
	s_nop 0
	v_add_f32_e32 v82, v194, v82
	v_add_f32_e32 v83, v195, v83
	s_nop 0
	v_add_f32_e32 v82, v192, v82
	v_add_f32_e32 v83, v193, v83
	s_nop 0
	v_add_f32_e32 v130, v190, v82
	v_add_f32_e32 v131, v191, v83
	v_add_u32_e32 v82, 0x3500, v236
	s_mov_b32 s17, s15
	s_waitcnt vmcnt(1)
	ds_write_b128 v237, v[122:125]
	s_waitcnt vmcnt(0)
	ds_write_b128 v237, v[126:129] offset:4608
	ds_write2_b64 v238, v[118:119], v[120:121] offset1:1
	ds_write2_b64 v82, v[114:115], v[116:117] offset1:1
	s_waitcnt lgkmcnt(0)
	s_barrier
	s_cbranch_vccnz .LBB0_405
	v_and_b32_e32 v51, 64, v233
	v_xor_b32_e32 v50, 32, v233
	v_add_u32_e32 v51, 64, v51
	v_cmp_lt_i32_e32 vcc, v50, v51
	v_mov_b32_e32 v163, v139
	s_cmpk_gt_i32 s16, 0x5ff
	v_cndmask_b32_e32 v50, v233, v50, vcc
	v_lshlrev_b32_e32 v51, 2, v50
	ds_bpermute_b32 v50, v51, v130
	ds_bpermute_b32 v52, v51, v131
	s_waitcnt lgkmcnt(1)
	v_add_f32_e32 v50, v130, v50
	v_div_scale_f32 v53, s[0:1], v50, v50, 1.0
	v_rcp_f32_e32 v54, v53
	v_div_scale_f32 v55, vcc, 1.0, v50, 1.0
	s_waitcnt lgkmcnt(0)
	v_add_f32_e32 v52, v131, v52
	v_fma_f32 v56, -v53, v54, 1.0
	v_fmac_f32_e32 v54, v56, v54
	v_mul_f32_e32 v56, v55, v54
	v_fma_f32 v57, -v53, v56, v55
	v_fmac_f32_e32 v56, v57, v54
	v_fma_f32 v53, -v53, v56, v55
	v_div_scale_f32 v55, s[0:1], v52, v52, v166
	v_rcp_f32_e32 v57, v55
	v_div_fmas_f32 v53, v53, v54, v56
	v_div_fixup_f32 v50, v53, v50, 1.0
	v_fma_f32 v53, -v55, v57, 1.0
	v_fmac_f32_e32 v57, v53, v57
	v_div_scale_f32 v53, vcc, v166, v52, v166
	v_mul_f32_e32 v54, v53, v57
	v_fma_f32 v56, -v55, v54, v53
	v_fmac_f32_e32 v54, v56, v57
	v_fma_f32 v53, -v55, v54, v53
	v_div_fmas_f32 v53, v53, v57, v54
	v_div_fixup_f32 v52, v53, v52, v166
	v_mul_f32_e32 v53, v66, v52
	v_fma_f32 v53, v34, v50, -v53
	v_mul_f32_e32 v34, v67, v52
	v_fma_f32 v54, v35, v50, -v34
	v_mul_f32_e32 v34, v68, v52
	v_fma_f32 v56, v36, v50, -v34
	v_mul_f32_e32 v34, v69, v52
	v_fma_f32 v57, v37, v50, -v34
	v_mul_f32_e32 v34, v70, v52
	v_fma_f32 v38, v38, v50, -v34
	v_mul_f32_e32 v34, v71, v52
	v_fma_f32 v39, v39, v50, -v34
	v_mul_f32_e32 v34, v72, v52
	v_fma_f32 v40, v40, v50, -v34
	v_mul_f32_e32 v34, v73, v52
	v_fma_f32 v41, v41, v50, -v34
	v_mul_f32_e32 v34, v74, v52
	v_fma_f32 v42, v42, v50, -v34
	v_mul_f32_e32 v34, v75, v52
	v_fma_f32 v43, v43, v50, -v34
	v_mul_f32_e32 v34, v76, v52
	v_fma_f32 v44, v44, v50, -v34
	global_load_dwordx4 v[34:37], v[148:149], off
	v_mul_f32_e32 v55, v54, v54
	v_fmac_f32_e32 v55, v53, v53
	v_fmac_f32_e32 v55, v56, v56
	v_fmac_f32_e32 v55, v57, v57
	v_fmac_f32_e32 v55, v38, v38
	v_fmac_f32_e32 v55, v39, v39
	v_fmac_f32_e32 v55, v40, v40
	v_fmac_f32_e32 v55, v41, v41
	v_fmac_f32_e32 v55, v42, v42
	v_fmac_f32_e32 v55, v43, v43
	v_mul_f32_e32 v58, v77, v52
	v_fmac_f32_e32 v55, v44, v44
	v_fma_f32 v45, v45, v50, -v58
	v_mul_f32_e32 v58, v78, v52
; __device__ __forceinline__ ConvD conv_expert_desc(const Params& P, int l, int it) {
;   ConvD d;
;   int kind = it / 8192, r = it % 8192;
;   int e = r / 512, q = r % 512;
;   if (kind < 2) {
;     int kt = q / 32, nt = q % 32;
;     d.src = (kind == 0 ? P.w_gate : P.w_up) + ((size_t)(l * 16 + e)) * DM * 2048 + (size_t)kt * 64 * 2048 + nt * 64;
;     d.ld = 2048;
;     d.dst = WSP(u16, OFF_WGU) + (size_t)e * 4096 * DM + ((size_t)kt * 4096 + nt * 128 + (kind ? 64 : 0)) * 64;
;     d.ldd = 64;
;   } else {
;     int kt = q / 16, nt = q % 16;
;     d.src = P.w_down + ((size_t)(l * 16 + e)) * 2048 * DM + (size_t)kt * 64 * DM + nt * 64;
;     d.ld = DM;
;     d.dst = WSP(u16, OFF_WDN) + (size_t)e * DM * 2048 + ((size_t)kt * 1024 + nt * 64) * 64;
;     d.ldd = 64;
; __device__ __forceinline__ void df_block(const Params& P, int l, int b, int qrow_blk, int h, int tk_lo, int tk_hi, char* smem) {
;     ...
;   float ss = 0.f;
; #pragma unroll
;   for (int m = 0; m < 2; ++m)
; #pragma unroll
;     for (int j = 0; j < 16; ++j) {
;       float v = o1[m][j] * r1 - o2[m][j] * r2;
;       o1[m][j] = v;
;       ss += v * v;
;     }
;   ss += __shfl_xor(ss, 32);
;   const float rinv = rsqrtf(ss * (1.f / 64.f) + EPS) * (1.f - lam_init);
;   const float* sg = P.df_subln_g + l * 64;
;   u16* dst = WSP(u16, OFF_ODF) + (size_t)qrow * 384 + h * 64;
; #pragma unroll
;   for (int m = 0; m < 2; ++m)
; #pragma unroll
;     for (int g = 0; g < 4; ++g) {
;       int dv = m * 32 + 8 * g + 4 * hh;
;       uint2 w;
;       w.x = pack2(o1[m][4 * g + 0] * rinv * sg[dv + 0], o1[m][4 * g + 1] * rinv * sg[dv + 1]);
;       w.y = pack2(o1[m][4 * g + 2] * rinv * sg[dv + 2], o1[m][4 * g + 3] * rinv * sg[dv + 3]);
;       *(uint2*)(dst + dv) = w;
;     }
; }
	v_fmac_f32_e32 v55, v45, v45
	v_fma_f32 v46, v46, v50, -v58
	v_mul_f32_e32 v58, v79, v52
	v_fmac_f32_e32 v55, v46, v46
	v_fma_f32 v47, v47, v50, -v58
	v_mul_f32_e32 v58, v80, v52
	v_fmac_f32_e32 v55, v47, v47
	v_fma_f32 v48, v48, v50, -v58
	v_mul_f32_e32 v58, v81, v52
	v_mul_f32_e32 v18, v18, v52
	v_fmac_f32_e32 v55, v48, v48
	v_fma_f32 v49, v49, v50, -v58
	v_fma_f32 v18, v2, v50, -v18
	v_mul_f32_e32 v2, v19, v52
	v_fmac_f32_e32 v55, v49, v49
	v_fma_f32 v19, v3, v50, -v2
	v_mul_f32_e32 v2, v20, v52
	v_fmac_f32_e32 v55, v18, v18
	v_fma_f32 v20, v4, v50, -v2
	v_mul_f32_e32 v2, v21, v52
	v_fmac_f32_e32 v55, v19, v19
	v_fma_f32 v21, v5, v50, -v2
	v_mul_f32_e32 v2, v22, v52
	v_fmac_f32_e32 v55, v20, v20
	v_fma_f32 v22, v6, v50, -v2
	v_mul_f32_e32 v2, v23, v52
	v_fmac_f32_e32 v55, v21, v21
	v_fma_f32 v23, v7, v50, -v2
	v_pk_mul_f32 v[2:3], v[24:25], v[52:53] op_sel_hi:[1,0]
	v_fmac_f32_e32 v55, v22, v22
	v_pk_fma_f32 v[6:7], v[8:9], v[50:51], v[2:3] op_sel_hi:[1,0,1] neg_lo:[0,0,1] neg_hi:[0,0,1]
	v_fmac_f32_e32 v55, v23, v23
	v_pk_mul_f32 v[2:3], v[6:7], v[6:7]
	s_nop 0
	v_add_f32_e32 v2, v2, v55
	v_add_f32_e32 v4, v3, v2
	v_pk_mul_f32 v[2:3], v[26:27], v[52:53] op_sel_hi:[1,0]
	s_nop 0
	v_pk_fma_f32 v[8:9], v[10:11], v[50:51], v[2:3] op_sel_hi:[1,0,1] neg_lo:[0,0,1] neg_hi:[0,0,1]
	s_nop 0
	v_pk_mul_f32 v[2:3], v[8:9], v[8:9]
	s_nop 0
	v_add_f32_e32 v2, v2, v4
	v_add_f32_e32 v4, v3, v2
	v_pk_mul_f32 v[2:3], v[28:29], v[52:53] op_sel_hi:[1,0]
	s_nop 0
	v_pk_fma_f32 v[10:11], v[12:13], v[50:51], v[2:3] op_sel_hi:[1,0,1] neg_lo:[0,0,1] neg_hi:[0,0,1]
	s_nop 0
	v_pk_mul_f32 v[2:3], v[10:11], v[10:11]
	s_nop 0
	v_add_f32_e32 v2, v2, v4
	v_add_f32_e32 v4, v3, v2
	v_pk_mul_f32 v[2:3], v[30:31], v[52:53] op_sel_hi:[1,0]
	s_nop 0
	v_pk_fma_f32 v[12:13], v[14:15], v[50:51], v[2:3] op_sel_hi:[1,0,1] neg_lo:[0,0,1] neg_hi:[0,0,1]
	s_nop 0
	v_pk_mul_f32 v[2:3], v[12:13], v[12:13]
	s_nop 0
	v_add_f32_e32 v2, v2, v4
	v_add_f32_e32 v4, v3, v2
	v_pk_mul_f32 v[2:3], v[32:33], v[52:53] op_sel_hi:[1,0]
	s_nop 0
	v_pk_fma_f32 v[14:15], v[16:17], v[50:51], v[2:3] op_sel_hi:[1,0,1] neg_lo:[0,0,1] neg_hi:[0,0,1]
	s_nop 0
	v_pk_mul_f32 v[2:3], v[14:15], v[14:15]
	s_nop 0
	v_add_f32_e32 v2, v2, v4
	v_add_f32_e32 v2, v3, v2
	ds_bpermute_b32 v3, v51, v2
	s_waitcnt lgkmcnt(0)
	v_add_f32_e32 v2, v2, v3
	v_fmamk_f32 v2, v2, 0x3c800000, v234
	v_mul_f32_e32 v3, 0x4b800000, v2
	v_cmp_gt_f32_e32 vcc, s35, v2
	s_nop 1
	v_cndmask_b32_e32 v2, v2, v3, vcc
	v_rsq_f32_e32 v2, v2
	s_nop 0
	v_mul_f32_e32 v3, 0x45800000, v2
	v_cndmask_b32_e32 v2, v2, v3, vcc
	v_sub_f32_e32 v3, 1.0, v167
	v_mul_f32_e32 v24, v3, v2
	v_mul_f32_e32 v4, v53, v24
	v_mul_f32_e32 v5, v54, v24
	s_waitcnt vmcnt(0)
	v_mul_f32_e32 v4, v34, v4
	v_mul_f32_e32 v5, v35, v5
	v_lshl_add_u64 v[2:3], s[8:9], 0, v[168:169]
	v_cvt_pk_bf16_f32 v4, v4, v5
	v_mul_f32_e32 v5, v56, v24
	v_mul_f32_e32 v16, v57, v24
	v_lshl_add_u64 v[2:3], s[12:13], 1, v[2:3]
	v_mul_f32_e32 v5, v36, v5
	v_mul_f32_e32 v16, v37, v16
	v_cvt_pk_bf16_f32 v5, v5, v16
	v_lshl_add_u64 v[16:17], v[2:3], 0, v[162:163]
	global_store_dwordx2 v[16:17], v[4:5], off
	global_load_dwordx4 v[2:5], v[148:149], off offset:32
	v_mul_f32_e32 v25, v38, v24
	v_mul_f32_e32 v26, v39, v24
	v_mul_f32_e32 v28, v41, v24
	v_mul_f32_e32 v27, v40, v24
	v_mul_f32_e32 v18, v18, v24
	v_mul_f32_e32 v19, v19, v24
	v_mul_f32_e32 v20, v20, v24
	v_mul_f32_e32 v21, v21, v24
	v_mul_f32_e32 v6, v6, v24
	v_mul_f32_e32 v7, v7, v24
	s_waitcnt vmcnt(0)
	v_mul_f32_e32 v2, v2, v25
	v_mul_f32_e32 v3, v3, v26
	v_cvt_pk_bf16_f32 v2, v2, v3
	v_mul_f32_e32 v3, v5, v28
	v_mul_f32_e32 v4, v4, v27
	v_cvt_pk_bf16_f32 v3, v4, v3
	global_store_dwordx2 v[16:17], v[2:3], off offset:16
	global_load_dwordx4 v[2:5], v[148:149], off offset:64
	v_mul_f32_e32 v25, v42, v24
	v_mul_f32_e32 v26, v43, v24
	v_mul_f32_e32 v27, v44, v24
	v_mul_f32_e32 v28, v45, v24
	s_waitcnt vmcnt(0)
	v_mul_f32_e32 v2, v2, v25
	v_mul_f32_e32 v3, v3, v26
	v_mul_f32_e32 v4, v4, v27
	v_mul_f32_e32 v5, v5, v28
	v_cvt_pk_bf16_f32 v2, v2, v3
	v_cvt_pk_bf16_f32 v3, v4, v5
	global_store_dwordx2 v[16:17], v[2:3], off offset:32
	global_load_dwordx4 v[2:5], v[148:149], off offset:96
	v_mul_f32_e32 v25, v46, v24
	v_mul_f32_e32 v26, v47, v24
	v_mul_f32_e32 v27, v48, v24
	v_mul_f32_e32 v28, v49, v24
	s_waitcnt vmcnt(0)
	v_mul_f32_e32 v2, v2, v25
	v_mul_f32_e32 v3, v3, v26
	v_mul_f32_e32 v4, v4, v27
	v_mul_f32_e32 v5, v5, v28
	v_cvt_pk_bf16_f32 v2, v2, v3
	v_cvt_pk_bf16_f32 v3, v4, v5
	global_store_dwordx2 v[16:17], v[2:3], off offset:48
	global_load_dwordx4 v[2:5], v[148:149], off offset:128
	s_waitcnt vmcnt(0)
	v_mul_f32_e32 v2, v2, v18
	v_mul_f32_e32 v3, v3, v19
	v_mul_f32_e32 v4, v4, v20
	v_mul_f32_e32 v5, v5, v21
	v_cvt_pk_bf16_f32 v2, v2, v3
	v_cvt_pk_bf16_f32 v3, v4, v5
	global_store_dwordx2 v[16:17], v[2:3], off offset:64
	global_load_dwordx4 v[2:5], v[148:149], off offset:160
	v_mul_f32_e32 v18, v22, v24
	v_mul_f32_e32 v19, v23, v24
	s_waitcnt vmcnt(0)
	v_mul_f32_e32 v2, v2, v18
	v_mul_f32_e32 v3, v3, v19
	v_mul_f32_e32 v4, v4, v6
	v_mul_f32_e32 v5, v5, v7
	v_cvt_pk_bf16_f32 v2, v2, v3
	v_cvt_pk_bf16_f32 v3, v4, v5
	global_store_dwordx2 v[16:17], v[2:3], off offset:80
	global_load_dwordx4 v[2:5], v[148:149], off offset:192
	v_mul_f32_e32 v6, v8, v24
	v_mul_f32_e32 v7, v9, v24
	v_mul_f32_e32 v8, v10, v24
	v_mul_f32_e32 v9, v11, v24
	s_waitcnt vmcnt(0)
	v_mul_f32_e32 v2, v6, v2
	v_mul_f32_e32 v3, v7, v3
	v_mul_f32_e32 v4, v8, v4
	v_mul_f32_e32 v5, v9, v5
	v_cvt_pk_bf16_f32 v2, v2, v3
	v_cvt_pk_bf16_f32 v3, v4, v5
	global_store_dwordx2 v[16:17], v[2:3], off offset:96
	global_load_dwordx4 v[2:5], v[148:149], off offset:224
	v_mul_f32_e32 v6, v12, v24
	v_mul_f32_e32 v7, v13, v24
	v_mul_f32_e32 v8, v14, v24
	v_mul_f32_e32 v9, v15, v24
	s_waitcnt vmcnt(0)
	v_mul_f32_e32 v2, v6, v2
	v_mul_f32_e32 v3, v7, v3
	v_mul_f32_e32 v4, v8, v4
	v_mul_f32_e32 v5, v9, v5
	v_cvt_pk_bf16_f32 v2, v2, v3
	v_cvt_pk_bf16_f32 v3, v4, v5
	global_store_dwordx2 v[16:17], v[2:3], off offset:112
	s_cbranch_scc1 .LBB0_419
	s_bfe_i32 s0, s16, 0x1001b
	s_lshl_b32 s36, s16, 4
	s_lshr_b32 s0, s0, 19
	s_add_i32 s0, s36, s0
	s_and_b32 s0, s0, 0xffffe000
	s_sub_i32 s0, s36, s0
	s_sext_i32_i16 s1, s0
	s_bfe_u32 s1, s1, 0x90016
	s_add_i32 s1, s0, s1
	s_sext_i32_i16 s10, s1
	s_and_b32 s1, s1, 0xfe00
	s_lshr_b32 s18, s10, 9
	s_sub_i32 s19, s0, s1
	s_cmpk_gt_i32 s16, 0x3ff
	s_mov_b64 s[16:17], -1
	s_cbranch_scc0 .LBB0_409
	s_and_b32 s10, s18, 0xffff
	s_and_b32 s16, 0xffff, s19
	s_lshl_b64 s[0:1], s[10:11], 23
	s_add_u32 s0, s54, s0
	s_addc_u32 s1, s55, s1
	s_lshl_b32 s12, s16, 14
	s_add_u32 s0, s0, s12
	s_addc_u32 s1, s1, 0
	s_lshl_b32 s12, s16, 6
	s_and_b32 s14, s12, 0x3c0
	s_lshl_b32 s12, s14, 2
	s_add_u32 s0, s0, s12
	s_addc_u32 s1, s1, 0
	s_lshl_b64 s[12:13], s[10:11], 22
	s_and_b32 s10, s13, 1
	s_add_u32 s12, s25, s12
	s_addc_u32 s10, s26, s10
	s_lshl_b32 s13, s16, 13
	s_add_u32 s12, s12, s13
	s_mov_b32 s15, s11
	s_addc_u32 s13, s10, 0
	s_mov_b64 s[16:17], 0

; __device__ __forceinline__ float fast_exp2(float x) { return __builtin_amdgcn_exp2f(x); }
; __device__ __forceinline__ void df_block(const Params& P, int l, int b, int qrow_blk, int h, int tk_lo, int tk_hi, char* smem) {
;     ...
;   for (int tk = tk_lo; tk < tk_hi; tk += 64) {
;     const int tn = (tk + 64 < tk_hi) ? tk + 64 : tk;
;     rk0 = *(const uint4*)(KD + (size_t)key_row(b, tn + lrow0) * 384 + h * 64 + lch * 8);
;     rk1 = *(const uint4*)(KD + (size_t)key_row(b, tn + lrow0 + 32) * 384 + h * 64 + lch * 8);
;     rv0 = *(const uint4*)(vsrc0 + tn);
;     rv1 = *(const uint4*)(vsrc1 + tn);
;     __builtin_amdgcn_sched_barrier(0);
;     const char* Ks = smem + cur * DF_BUF;
;     const char* Vs = Ks + DF_KBYTES;
; #pragma unroll
;     for (int sub = 0; sub < 2; ++sub) {
;       const char* kp = Ks + (sub * 32 + ql) * DF_KSTR + hh * 16;
;       bf16x8 pa0, pa1, pb0, pb1;
;       {
;         f32x16 S = mfma32(*(const bf16x8*)(kp), q1[0], cini);
;         S = mfma32(*(const bf16x8*)(kp + 32), q1[1], S);
;         float p[16];
; #pragma unroll
;         for (int j = 0; j < 16; ++j) { p[j] = fast_exp2(S[j]); l1 += p[j]; }
;         pack_p(p, pa0, pa1);
;       }
;       {
;         f32x16 S = mfma32(*(const bf16x8*)(kp + 64), q2[0], cini);
;         S = mfma32(*(const bf16x8*)(kp + 96), q2[1], S);
;         float p[16];
; #pragma unroll
;         for (int j = 0; j < 16; ++j) { p[j] = fast_exp2(S[j]); l2 += p[j]; }
;         pack_p(p, pb0, pb1);
;       }
; #pragma unroll
;       for (int s2 = 0; s2 < 2; ++s2) {
;         const char* vp0 = Vs + ql * DF_VSTR + (sub * 32 + 16 * s2 + 4 * hh) * 2;
;         const char* vp1 = vp0 + 32 * DF_VSTR;
;         union { uint4 u; bf16x8 v; } c0, c1;
;         uint2 a0 = *(const uint2*)(vp0), a1 = *(const uint2*)(vp0 + 16);
;         uint2 e0 = *(const uint2*)(vp1), e1 = *(const uint2*)(vp1 + 16);
;         c0.u = make_uint4(a0.x, a0.y, a1.x, a1.y);
;         c1.u = make_uint4(e0.x, e0.y, e1.x, e1.y);
;         o1[0] = mfma32(c0.v, s2 ? pa1 : pa0, o1[0]);
;         o1[1] = mfma32(c1.v, s2 ? pa1 : pa0, o1[1]);
;         o2[0] = mfma32(c0.v, s2 ? pb1 : pb0, o2[0]);
;         o2[1] = mfma32(c1.v, s2 ? pb1 : pb0, o2[1]);
;       }
;     }
.LBB0_1434:
	s_add_i32 s18, s0, 64
	s_cmpk_lt_u32 s0, 0x10c0
	s_cselect_b64 s[20:21], -1, 0
	s_and_b64 vcc, s[20:21], exec
	s_cselect_b32 s12, s18, s0
	v_add_u32_e32 v86, s12, v135
	v_cmp_gt_u32_e64 s[0:1], s31, v86
	s_lshl_b64 s[20:21], s[12:13], 1
	v_lshl_add_u64 v[82:83], v[170:171], 0, s[20:21]
	v_cndmask_b32_e64 v87, v163, v140, s[0:1]
	v_cmp_gt_u32_e64 s[0:1], s34, v86
	v_add_u32_e32 v87, v87, v86
	v_lshl_add_u64 v[84:85], v[172:173], 0, s[20:21]
	v_cndmask_b32_e64 v88, v165, v235, s[0:1]
	v_add_u32_e32 v86, v88, v86
	global_load_dwordx4 v[118:121], v[82:83], off
	global_load_dwordx4 v[114:117], v[84:85], off
	v_mad_i64_i32 v[82:83], s[0:1], v87, s29, v[174:175]
	v_mad_i64_i32 v[84:85], s[0:1], v86, s29, v[174:175]
	global_load_dwordx4 v[122:125], v[82:83], off
	global_load_dwordx4 v[126:129], v[84:85], off
	s_mul_i32 s0, s17, 0x4600
	s_xor_b32 s17, s17, 1
	v_or_b32_e32 v82, s0, v142
	v_add3_u32 v218, s0, v139, v138
	s_mul_i32 s0, s17, 0x4600
	v_add_u32_e32 v236, s0, v143
	v_add_u32_e32 v219, v82, v145
	v_add_u32_e32 v237, s0, v137
	v_add_u32_e32 v238, 0x2400, v236
	ds_read_b128 v[176:179], v219
	ds_read_b128 v[180:183], v219 offset:32
	ds_read_b128 v[196:199], v219 offset:64
	v_add_u32_e32 v239, 0x2000, v218
	v_add_u32_e32 v248, 0x3000, v218
	s_waitcnt vmcnt(7) lgkmcnt(2)
	v_mfma_f32_32x32x16_bf16 v[82:97], v[176:179], v[98:101], v[66:81]
	s_waitcnt vmcnt(4) lgkmcnt(1)
	v_mfma_f32_32x32x16_bf16 v[82:97], v[180:183], v[110:113], v[82:97]
	s_nop 11
	v_exp_f32_e32 v132, v82
	v_exp_f32_e32 v200, v83
	v_exp_f32_e32 v202, v84
	v_exp_f32_e32 v204, v85
	v_exp_f32_e32 v206, v86
	v_exp_f32_e32 v208, v87
	v_exp_f32_e32 v210, v88
	v_exp_f32_e32 v212, v89
	v_exp_f32_e32 v214, v90
	v_exp_f32_e32 v216, v91
	v_exp_f32_e32 v186, v92
	v_exp_f32_e32 v184, v93
	v_exp_f32_e32 v182, v94
	v_exp_f32_e32 v180, v95
	v_exp_f32_e32 v178, v96
	v_exp_f32_e32 v176, v97
	s_waitcnt lgkmcnt(0)
	v_mfma_f32_32x32x16_bf16 v[82:97], v[196:199], v[106:109], v[66:81]
	ds_read_b128 v[196:199], v219 offset:96
	v_cvt_pk_bf16_f32 v188, v132, v200
	v_cvt_pk_bf16_f32 v189, v202, v204
	v_cvt_pk_bf16_f32 v190, v206, v208
	v_cvt_pk_bf16_f32 v191, v210, v212
	v_cvt_pk_bf16_f32 v192, v214, v216
	v_cvt_pk_bf16_f32 v193, v186, v184
	s_waitcnt lgkmcnt(0)
	v_mfma_f32_32x32x16_bf16 v[82:97], v[196:199], v[102:105], v[82:97]
	v_cvt_pk_bf16_f32 v194, v182, v180
	v_cvt_pk_bf16_f32 v195, v178, v176
	s_nop 11
	v_exp_f32_e32 v215, v90
	v_exp_f32_e32 v217, v91
	v_exp_f32_e32 v187, v92
	v_exp_f32_e32 v185, v93
	v_exp_f32_e32 v183, v94
	v_exp_f32_e32 v181, v95
	v_exp_f32_e32 v179, v96
	v_exp_f32_e32 v177, v97
	ds_read2_b64 v[90:93], v239 offset0:128 offset1:130
	ds_read2_b64 v[94:97], v239 offset0:132 offset1:134
	ds_read2_b64 v[196:199], v248 offset0:160 offset1:162
	v_exp_f32_e32 v133, v82
	v_exp_f32_e32 v201, v83
	v_exp_f32_e32 v203, v84
	v_exp_f32_e32 v205, v85
	v_exp_f32_e32 v207, v86
	v_exp_f32_e32 v209, v87
	v_exp_f32_e32 v211, v88
	v_exp_f32_e32 v213, v89
	v_cvt_pk_bf16_f32 v82, v133, v201
	v_cvt_pk_bf16_f32 v83, v203, v205
	v_cvt_pk_bf16_f32 v84, v207, v209
	v_cvt_pk_bf16_f32 v85, v211, v213
	s_waitcnt lgkmcnt(0)
	v_mfma_f32_32x32x16_bf16 v[2:17], v[196:199], v[188:191], v[2:17]
	v_cvt_pk_bf16_f32 v86, v215, v217
	v_cvt_pk_bf16_f32 v87, v187, v185
	v_cvt_pk_bf16_f32 v88, v183, v181
	v_cvt_pk_bf16_f32 v89, v179, v177
	ds_read_b128 v[244:247], v219 offset:4672
	v_mfma_f32_32x32x16_bf16 v[50:65], v[90:93], v[82:85], v[50:65]
	v_mfma_f32_32x32x16_bf16 v[18:33], v[196:199], v[82:85], v[18:33]
	ds_read2_b64 v[82:85], v248 offset0:164 offset1:166
	s_waitcnt lgkmcnt(0)
	v_mfma_f32_32x32x16_bf16 v[2:17], v[82:85], v[192:195], v[2:17]
	v_mfma_f32_32x32x16_bf16 v[18:33], v[82:85], v[86:89], v[18:33]
	v_add_f32_e64 v82, v130, v132
	v_add_f32_e64 v83, v131, v133
	ds_read_b128 v[130:133], v219 offset:4608
	v_add_f32_e64 v82, v200, v82
	v_add_f32_e64 v83, v201, v83
	v_add_f32_e32 v82, v202, v82
	v_add_f32_e32 v83, v203, v83
	s_nop 0
	v_add_f32_e32 v82, v204, v82
	v_add_f32_e32 v83, v205, v83
	v_mfma_f32_32x32x16_bf16 v[34:49], v[90:93], v[188:191], v[34:49]
	v_add_f32_e64 v82, v206, v82
	v_add_f32_e64 v83, v207, v83
	v_add_f32_e64 v82, v208, v82
	v_add_f32_e64 v83, v209, v83
	v_add_f32_e64 v82, v210, v82
	v_add_f32_e64 v83, v211, v83
	v_add_f32_e32 v82, v212, v82
	v_add_f32_e32 v83, v213, v83
	v_mfma_f32_32x32x16_bf16 v[34:49], v[94:97], v[192:195], v[34:49]
	v_add_f32_e64 v82, v214, v82
	v_add_f32_e64 v83, v215, v83
	v_add_f32_e64 v188, v216, v82
	v_add_f32_e64 v189, v217, v83
	v_mfma_f32_32x32x16_bf16 v[50:65], v[94:97], v[86:89], v[50:65]
	s_waitcnt lgkmcnt(0)
	v_mfma_f32_32x32x16_bf16 v[82:97], v[130:133], v[98:101], v[66:81]
	ds_read_b128 v[130:133], v219 offset:4640
	s_waitcnt lgkmcnt(0)
	v_mfma_f32_32x32x16_bf16 v[82:97], v[130:133], v[110:113], v[82:97]
	s_nop 11
	v_exp_f32_e32 v220, v82
	v_exp_f32_e32 v218, v83
	v_exp_f32_e32 v216, v84
	v_exp_f32_e32 v214, v85
	v_exp_f32_e32 v212, v86
	v_exp_f32_e32 v210, v87
	v_exp_f32_e32 v208, v88
	v_exp_f32_e32 v206, v89
	v_exp_f32_e32 v204, v90
	v_exp_f32_e32 v202, v91
	v_exp_f32_e32 v200, v92
	v_exp_f32_e32 v198, v93
	v_exp_f32_e32 v196, v94
	v_exp_f32_e32 v194, v95
	v_exp_f32_e32 v192, v96
	v_exp_f32_e32 v190, v97
	v_mfma_f32_32x32x16_bf16 v[82:97], v[244:247], v[106:109], v[66:81]
	ds_read_b128 v[244:247], v219 offset:4704
	v_cvt_pk_bf16_f32 v240, v220, v218
	v_cvt_pk_bf16_f32 v241, v216, v214
	v_cvt_pk_bf16_f32 v242, v212, v210
	v_cvt_pk_bf16_f32 v243, v208, v206
	v_cvt_pk_bf16_f32 v130, v204, v202
	v_cvt_pk_bf16_f32 v131, v200, v198
	s_waitcnt lgkmcnt(0)
; __device__ __forceinline__ float fast_exp2(float x) { return __builtin_amdgcn_exp2f(x); }
; __device__ __forceinline__ void df_block(const Params& P, int l, int b, int qrow_blk, int h, int tk_lo, int tk_hi, char* smem) {
;     ...
;         for (int j = 0; j < 16; ++j) { p[j] = fast_exp2(S[j]); l1 += p[j]; }
;         pack_p(p, pa0, pa1);
;       }
;       {
;         f32x16 S = mfma32(*(const bf16x8*)(kp + 64), q2[0], cini);
;         S = mfma32(*(const bf16x8*)(kp + 96), q2[1], S);
;         float p[16];
; #pragma unroll
;         for (int j = 0; j < 16; ++j) { p[j] = fast_exp2(S[j]); l2 += p[j]; }
;         pack_p(p, pb0, pb1);
;       }
; #pragma unroll
;       for (int s2 = 0; s2 < 2; ++s2) {
;         const char* vp0 = Vs + ql * DF_VSTR + (sub * 32 + 16 * s2 + 4 * hh) * 2;
;         const char* vp1 = vp0 + 32 * DF_VSTR;
;         union { uint4 u; bf16x8 v; } c0, c1;
;         uint2 a0 = *(const uint2*)(vp0), a1 = *(const uint2*)(vp0 + 16);
;         uint2 e0 = *(const uint2*)(vp1), e1 = *(const uint2*)(vp1 + 16);
;         c0.u = make_uint4(a0.x, a0.y, a1.x, a1.y);
;         c1.u = make_uint4(e0.x, e0.y, e1.x, e1.y);
;         o1[0] = mfma32(c0.v, s2 ? pa1 : pa0, o1[0]);
;         o1[1] = mfma32(c1.v, s2 ? pa1 : pa0, o1[1]);
;         o2[0] = mfma32(c0.v, s2 ? pb1 : pb0, o2[0]);
;         o2[1] = mfma32(c1.v, s2 ? pb1 : pb0, o2[1]);
;       }
;     }
;     __builtin_amdgcn_sched_barrier(0);
;     {
;       char* d = smem + (cur ^ 1) * DF_BUF;
;       *(uint4*)(d + koff0) = rk0;
;       *(uint4*)(d + koff1) = rk1;
;       *(uint2*)(d + voff0) = make_uint2(rv0.x, rv0.y); *(uint2*)(d + voff0 + 8) = make_uint2(rv0.z, rv0.w);
;       *(uint2*)(d + voff1) = make_uint2(rv1.x, rv1.y); *(uint2*)(d + voff1 + 8) = make_uint2(rv1.z, rv1.w);
;     }
;     __syncthreads();
;     cur ^= 1;
;   }
;   l1 += __shfl_xor(l1, 32);
;   l2 += __shfl_xor(l2, 32);
;   const float r1 = 1.f / l1, r2 = lam / l2;
;   float ss = 0.f;
; #pragma unroll
;   for (int m = 0; m < 2; ++m)
; #pragma unroll
;     for (int j = 0; j < 16; ++j) {
;       float v = o1[m][j] * r1 - o2[m][j] * r2;
;       o1[m][j] = v;
;       ss += v * v;
;     }
	v_mfma_f32_32x32x16_bf16 v[82:97], v[244:247], v[102:105], v[82:97]
	v_cvt_pk_bf16_f32 v132, v196, v194
	v_cvt_pk_bf16_f32 v133, v192, v190
	s_nop 11
	v_exp_f32_e32 v205, v90
	v_exp_f32_e32 v203, v91
	v_exp_f32_e32 v201, v92
	v_exp_f32_e32 v199, v93
	v_exp_f32_e32 v197, v94
	v_exp_f32_e32 v195, v95
	v_exp_f32_e32 v193, v96
	v_exp_f32_e32 v191, v97
	ds_read2_b64 v[90:93], v239 offset0:136 offset1:138
	ds_read2_b64 v[94:97], v248 offset0:168 offset1:170
	v_exp_f32_e32 v221, v82
	v_exp_f32_e32 v219, v83
	v_exp_f32_e32 v217, v84
	v_exp_f32_e32 v215, v85
	v_exp_f32_e32 v213, v86
	v_exp_f32_e32 v211, v87
	v_exp_f32_e32 v209, v88
	v_exp_f32_e32 v207, v89
	v_cvt_pk_bf16_f32 v86, v221, v219
	v_cvt_pk_bf16_f32 v87, v217, v215
	v_cvt_pk_bf16_f32 v88, v213, v211
	v_cvt_pk_bf16_f32 v89, v209, v207
	s_waitcnt lgkmcnt(1)
	v_mfma_f32_32x32x16_bf16 v[34:49], v[90:93], v[240:243], v[34:49]
	v_cvt_pk_bf16_f32 v82, v205, v203
	v_cvt_pk_bf16_f32 v83, v201, v199
	v_cvt_pk_bf16_f32 v84, v197, v195
	v_cvt_pk_bf16_f32 v85, v193, v191
	v_mfma_f32_32x32x16_bf16 v[50:65], v[90:93], v[86:89], v[50:65]
	s_waitcnt lgkmcnt(0)
	v_mfma_f32_32x32x16_bf16 v[18:33], v[94:97], v[86:89], v[18:33]
	ds_read2_b64 v[86:89], v239 offset0:140 offset1:142
	ds_read2_b64 v[90:93], v248 offset0:172 offset1:174
	s_waitcnt lgkmcnt(1)
	v_mfma_f32_32x32x16_bf16 v[50:65], v[86:89], v[82:85], v[50:65]
	s_waitcnt lgkmcnt(0)
	v_mfma_f32_32x32x16_bf16 v[18:33], v[90:93], v[82:85], v[18:33]
	v_add_f32_e64 v82, v186, v188
	v_add_f32_e64 v83, v187, v189
	v_add_f32_e64 v82, v184, v82
	v_add_f32_e64 v83, v185, v83
	v_add_f32_e64 v82, v182, v82
	v_add_f32_e64 v83, v183, v83
	v_add_f32_e32 v82, v180, v82
	v_add_f32_e32 v83, v181, v83
	v_mfma_f32_32x32x16_bf16 v[2:17], v[94:97], v[240:243], v[2:17]
	v_add_f32_e64 v82, v178, v82
	v_add_f32_e64 v83, v179, v83
	v_add_f32_e64 v82, v176, v82
	v_add_f32_e64 v83, v177, v83
	v_add_f32_e64 v82, v82, v220
	v_add_f32_e64 v83, v83, v221
	v_add_f32_e32 v82, v218, v82
	v_add_f32_e32 v83, v219, v83
	v_mfma_f32_32x32x16_bf16 v[34:49], v[86:89], v[130:133], v[34:49]
	v_add_f32_e64 v82, v216, v82
	v_add_f32_e64 v83, v217, v83
	v_add_f32_e64 v82, v214, v82
	v_add_f32_e64 v83, v215, v83
	v_add_f32_e64 v82, v212, v82
	v_add_f32_e64 v83, v213, v83
	v_add_f32_e32 v82, v210, v82
	v_add_f32_e32 v83, v211, v83
	v_mfma_f32_32x32x16_bf16 v[2:17], v[90:93], v[130:133], v[2:17]
	v_add_f32_e64 v82, v208, v82
	v_add_f32_e64 v83, v209, v83
	v_add_f32_e64 v82, v206, v82
	v_add_f32_e64 v83, v207, v83
	v_add_f32_e64 v82, v204, v82
	v_add_f32_e64 v83, v205, v83
	v_add_f32_e32 v82, v202, v82
	v_add_f32_e32 v83, v203, v83
	s_nop 0
	v_add_f32_e32 v82, v200, v82
	v_add_f32_e32 v83, v201, v83
	s_nop 0
	v_add_f32_e32 v82, v198, v82
	v_add_f32_e32 v83, v199, v83
	s_nop 0
	v_add_f32_e32 v82, v196, v82
	v_add_f32_e32 v83, v197, v83
	s_nop 0
	v_add_f32_e32 v82, v194, v82
	v_add_f32_e32 v83, v195, v83
	s_nop 0
	v_add_f32_e32 v82, v192, v82
	v_add_f32_e32 v83, v193, v83
	s_nop 0
	v_add_f32_e32 v130, v190, v82
	v_add_f32_e32 v131, v191, v83
	v_add_u32_e32 v82, 0x3500, v236
	s_mov_b32 s0, s18
	s_waitcnt vmcnt(1)
	ds_write_b128 v237, v[122:125]
	s_waitcnt vmcnt(0)
	ds_write_b128 v237, v[126:129] offset:4608
	ds_write2_b64 v238, v[118:119], v[120:121] offset1:1
	ds_write2_b64 v82, v[114:115], v[116:117] offset1:1
	s_waitcnt lgkmcnt(0)
	s_barrier
	s_cbranch_vccnz .LBB0_1434
	v_and_b32_e32 v67, 64, v233
	v_xor_b32_e32 v66, 32, v233
	v_add_u32_e32 v67, 64, v67
	v_cmp_lt_i32_e32 vcc, v66, v67
	v_mov_b32_e32 v163, v141
	s_lshl_b32 s33, s16, 4
	v_cndmask_b32_e32 v66, v233, v66, vcc
	v_lshlrev_b32_e32 v67, 2, v66
	ds_bpermute_b32 v66, v67, v130
	ds_bpermute_b32 v68, v67, v131
	s_mov_b64 s[20:21], -1
	s_waitcnt lgkmcnt(1)
	v_add_f32_e32 v66, v130, v66
	v_div_scale_f32 v69, s[0:1], v66, v66, 1.0
	v_rcp_f32_e32 v70, v69
	v_div_scale_f32 v71, vcc, 1.0, v66, 1.0
	s_waitcnt lgkmcnt(0)
	v_add_f32_e32 v68, v131, v68
	v_fma_f32 v72, -v69, v70, 1.0
	v_fmac_f32_e32 v70, v72, v70
	v_mul_f32_e32 v72, v71, v70
	v_fma_f32 v73, -v69, v72, v71
	v_fmac_f32_e32 v72, v73, v70
	v_fma_f32 v69, -v69, v72, v71
	v_div_scale_f32 v71, s[0:1], v68, v68, v166
	v_rcp_f32_e32 v73, v71
	v_div_fmas_f32 v69, v69, v70, v72
	v_div_fixup_f32 v66, v69, v66, 1.0
	s_bfe_i32 s0, s16, 0x1001b
	v_fma_f32 v69, -v71, v73, 1.0
	v_fmac_f32_e32 v73, v69, v73
	v_div_scale_f32 v69, vcc, v166, v68, v166
	v_mul_f32_e32 v70, v69, v73
	v_fma_f32 v72, -v71, v70, v69
	v_fmac_f32_e32 v70, v72, v73
	v_fma_f32 v69, -v71, v70, v69
	v_div_fmas_f32 v69, v69, v73, v70
	v_div_fixup_f32 v68, v69, v68, v166
	v_mul_f32_e32 v50, v50, v68
	v_fma_f32 v50, v34, v66, -v50
	v_mul_f32_e32 v34, v51, v68
	v_fma_f32 v51, v35, v66, -v34
	v_mul_f32_e32 v34, v52, v68
	v_fma_f32 v52, v36, v66, -v34
	v_mul_f32_e32 v34, v53, v68
	v_fma_f32 v53, v37, v66, -v34
	v_mul_f32_e32 v34, v54, v68
	v_fma_f32 v38, v38, v66, -v34
	v_mul_f32_e32 v34, v55, v68
	v_fma_f32 v39, v39, v66, -v34
	v_mul_f32_e32 v34, v56, v68
	v_fma_f32 v40, v40, v66, -v34
	v_mul_f32_e32 v34, v57, v68
	v_fma_f32 v41, v41, v66, -v34
	v_mul_f32_e32 v34, v58, v68
	v_fma_f32 v42, v42, v66, -v34
	v_mul_f32_e32 v34, v59, v68
	v_fma_f32 v43, v43, v66, -v34
	v_mul_f32_e32 v34, v60, v68
	v_fma_f32 v44, v44, v66, -v34
	global_load_dwordx4 v[34:37], v[150:151], off offset:256
	v_mul_f32_e32 v69, v51, v51
	v_fmac_f32_e32 v69, v50, v50
	v_fmac_f32_e32 v69, v52, v52
	v_fmac_f32_e32 v69, v53, v53
	v_fmac_f32_e32 v69, v38, v38
	v_fmac_f32_e32 v69, v39, v39
	v_fmac_f32_e32 v69, v40, v40
	v_fmac_f32_e32 v69, v41, v41
	v_fmac_f32_e32 v69, v42, v42
	v_fmac_f32_e32 v69, v43, v43
	v_mul_f32_e32 v54, v61, v68
	v_fmac_f32_e32 v69, v44, v44
; __device__ __forceinline__ ConvD conv_expert_desc(const Params& P, int l, int it) {
;   ConvD d;
;   int kind = it / 8192, r = it % 8192;
;   int e = r / 512, q = r % 512;
;   if (kind < 2) {
;     int kt = q / 32, nt = q % 32;
;     d.src = (kind == 0 ? P.w_gate : P.w_up) + ((size_t)(l * 16 + e)) * DM * 2048 + (size_t)kt * 64 * 2048 + nt * 64;
;     d.ld = 2048;
;     d.dst = WSP(u16, OFF_WGU) + (size_t)e * 4096 * DM + ((size_t)kt * 4096 + nt * 128 + (kind ? 64 : 0)) * 64;
;     d.ldd = 64;
;   } else {
;     int kt = q / 16, nt = q % 16;
;     d.src = P.w_down + ((size_t)(l * 16 + e)) * 2048 * DM + (size_t)kt * 64 * DM + nt * 64;
;     d.ld = DM;
;     d.dst = WSP(u16, OFF_WDN) + (size_t)e * DM * 2048 + ((size_t)kt * 1024 + nt * 64) * 64;
;     d.ldd = 64;
; __device__ __forceinline__ void df_block(const Params& P, int l, int b, int qrow_blk, int h, int tk_lo, int tk_hi, char* smem) {
;     ...
; #pragma unroll
;   for (int m = 0; m < 2; ++m)
; #pragma unroll
;     for (int j = 0; j < 16; ++j) {
;       float v = o1[m][j] * r1 - o2[m][j] * r2;
;       o1[m][j] = v;
;       ss += v * v;
;     }
;   ss += __shfl_xor(ss, 32);
;   const float rinv = rsqrtf(ss * (1.f / 64.f) + EPS) * (1.f - lam_init);
;   const float* sg = P.df_subln_g + l * 64;
;   u16* dst = WSP(u16, OFF_ODF) + (size_t)qrow * 384 + h * 64;
; #pragma unroll
;   for (int m = 0; m < 2; ++m)
; #pragma unroll
;     for (int g = 0; g < 4; ++g) {
;       int dv = m * 32 + 8 * g + 4 * hh;
;       uint2 w;
;       w.x = pack2(o1[m][4 * g + 0] * rinv * sg[dv + 0], o1[m][4 * g + 1] * rinv * sg[dv + 1]);
;       w.y = pack2(o1[m][4 * g + 2] * rinv * sg[dv + 2], o1[m][4 * g + 3] * rinv * sg[dv + 3]);
;       *(uint2*)(dst + dv) = w;
;     }
; }
	v_fma_f32 v45, v45, v66, -v54
	v_mul_f32_e32 v54, v62, v68
	v_fmac_f32_e32 v69, v45, v45
	v_fma_f32 v46, v46, v66, -v54
	v_mul_f32_e32 v54, v63, v68
	v_fmac_f32_e32 v69, v46, v46
	v_fma_f32 v47, v47, v66, -v54
	v_mul_f32_e32 v54, v64, v68
	v_fmac_f32_e32 v69, v47, v47
	v_fma_f32 v48, v48, v66, -v54
	v_mul_f32_e32 v54, v65, v68
	v_fmac_f32_e32 v69, v48, v48
	v_fma_f32 v49, v49, v66, -v54
	v_mul_f32_e32 v18, v18, v68
	v_fmac_f32_e32 v69, v49, v49
	v_fma_f32 v18, v2, v66, -v18
	v_mul_f32_e32 v2, v19, v68
	v_fmac_f32_e32 v69, v18, v18
	v_fma_f32 v19, v3, v66, -v2
	v_mul_f32_e32 v2, v20, v68
	v_fmac_f32_e32 v69, v19, v19
	v_fma_f32 v20, v4, v66, -v2
	v_mul_f32_e32 v2, v21, v68
	v_fmac_f32_e32 v69, v20, v20
	v_fma_f32 v21, v5, v66, -v2
	v_mul_f32_e32 v2, v22, v68
	v_fmac_f32_e32 v69, v21, v21
	v_fma_f32 v22, v6, v66, -v2
	v_mul_f32_e32 v2, v23, v68
	v_fmac_f32_e32 v69, v22, v22
	v_fma_f32 v23, v7, v66, -v2
	v_fmac_f32_e32 v69, v23, v23
	v_pk_mul_f32 v[2:3], v[24:25], v[68:69] op_sel_hi:[1,0]
	s_lshr_b32 s0, s0, 19
	v_pk_fma_f32 v[6:7], v[8:9], v[66:67], v[2:3] op_sel_hi:[1,0,1] neg_lo:[0,0,1] neg_hi:[0,0,1]
	s_add_i32 s0, s33, s0
	v_pk_mul_f32 v[2:3], v[6:7], v[6:7]
	s_and_b32 s0, s0, 0xffffe000
	v_add_f32_e32 v2, v2, v69
	v_add_f32_e32 v4, v3, v2
	v_pk_mul_f32 v[2:3], v[26:27], v[68:69] op_sel_hi:[1,0]
	s_sub_i32 s1, s33, s0
	v_pk_fma_f32 v[8:9], v[10:11], v[66:67], v[2:3] op_sel_hi:[1,0,1] neg_lo:[0,0,1] neg_hi:[0,0,1]
	s_sext_i32_i16 s0, s1
	v_pk_mul_f32 v[2:3], v[8:9], v[8:9]
	s_bfe_u32 s0, s0, 0x90016
	v_add_f32_e32 v2, v2, v4
	v_add_f32_e32 v4, v3, v2
	v_pk_mul_f32 v[2:3], v[28:29], v[68:69] op_sel_hi:[1,0]
	s_add_i32 s0, s1, s0
	v_pk_fma_f32 v[10:11], v[12:13], v[66:67], v[2:3] op_sel_hi:[1,0,1] neg_lo:[0,0,1] neg_hi:[0,0,1]
	s_sext_i32_i16 s12, s0
	v_pk_mul_f32 v[2:3], v[10:11], v[10:11]
	s_nop 0
	v_add_f32_e32 v2, v2, v4
	v_add_f32_e32 v4, v3, v2
	v_pk_mul_f32 v[2:3], v[30:31], v[68:69] op_sel_hi:[1,0]
	s_nop 0
	v_pk_fma_f32 v[12:13], v[14:15], v[66:67], v[2:3] op_sel_hi:[1,0,1] neg_lo:[0,0,1] neg_hi:[0,0,1]
	s_nop 0
	v_pk_mul_f32 v[2:3], v[12:13], v[12:13]
	s_nop 0
	v_add_f32_e32 v2, v2, v4
	v_add_f32_e32 v4, v3, v2
	v_pk_mul_f32 v[2:3], v[32:33], v[68:69] op_sel_hi:[1,0]
	s_nop 0
	v_pk_fma_f32 v[14:15], v[16:17], v[66:67], v[2:3] op_sel_hi:[1,0,1] neg_lo:[0,0,1] neg_hi:[0,0,1]
	s_nop 0
	v_pk_mul_f32 v[2:3], v[14:15], v[14:15]
	s_nop 0
	v_add_f32_e32 v2, v2, v4
	v_add_f32_e32 v2, v3, v2
	ds_bpermute_b32 v3, v67, v2
	s_waitcnt lgkmcnt(0)
	v_add_f32_e32 v2, v2, v3
	v_fmamk_f32 v2, v2, 0x3c800000, v234
	v_mul_f32_e32 v3, 0x4b800000, v2
	v_cmp_gt_f32_e32 vcc, s35, v2
	s_nop 1
	v_cndmask_b32_e32 v2, v2, v3, vcc
	v_rsq_f32_e32 v2, v2
	s_nop 0
	v_mul_f32_e32 v3, 0x45800000, v2
	v_cndmask_b32_e32 v2, v2, v3, vcc
	v_sub_f32_e32 v3, 1.0, v167
	v_mul_f32_e32 v24, v3, v2
	v_mul_f32_e32 v4, v50, v24
	v_mul_f32_e32 v5, v51, v24
	s_waitcnt vmcnt(0)
	v_mul_f32_e32 v4, v34, v4
	v_mul_f32_e32 v5, v35, v5
	v_lshl_add_u64 v[2:3], s[8:9], 0, v[168:169]
	v_cvt_pk_bf16_f32 v4, v4, v5
	v_mul_f32_e32 v5, v52, v24
	v_mul_f32_e32 v16, v53, v24
	v_lshl_add_u64 v[2:3], s[14:15], 1, v[2:3]
	v_mul_f32_e32 v5, v36, v5
	v_mul_f32_e32 v16, v37, v16
	v_cvt_pk_bf16_f32 v5, v5, v16
	v_lshl_add_u64 v[16:17], v[2:3], 0, v[162:163]
	global_store_dwordx2 v[16:17], v[4:5], off
	global_load_dwordx4 v[2:5], v[150:151], off offset:288
	v_mul_f32_e32 v25, v38, v24
	v_mul_f32_e32 v26, v39, v24
	v_mul_f32_e32 v28, v41, v24
	v_mul_f32_e32 v27, v40, v24
	v_mul_f32_e32 v18, v18, v24
	v_mul_f32_e32 v19, v19, v24
	v_mul_f32_e32 v20, v20, v24
	v_mul_f32_e32 v21, v21, v24
	v_mul_f32_e32 v6, v6, v24
	v_mul_f32_e32 v7, v7, v24
	s_and_b32 s14, s0, 0xfe00
	s_ashr_i32 s0, s12, 9
	s_sub_i32 s1, s1, s14
	s_cmpk_gt_i32 s16, 0x3ff
	s_waitcnt vmcnt(0)
	v_mul_f32_e32 v2, v2, v25
	v_mul_f32_e32 v3, v3, v26
	v_cvt_pk_bf16_f32 v2, v2, v3
	v_mul_f32_e32 v3, v5, v28
	v_mul_f32_e32 v4, v4, v27
	v_cvt_pk_bf16_f32 v3, v4, v3
	global_store_dwordx2 v[16:17], v[2:3], off offset:16
	global_load_dwordx4 v[2:5], v[150:151], off offset:320
	v_mul_f32_e32 v25, v42, v24
	v_mul_f32_e32 v26, v43, v24
	v_mul_f32_e32 v27, v44, v24
	v_mul_f32_e32 v28, v45, v24
	s_waitcnt vmcnt(0)
	v_mul_f32_e32 v2, v2, v25
	v_mul_f32_e32 v3, v3, v26
	v_mul_f32_e32 v4, v4, v27
	v_mul_f32_e32 v5, v5, v28
	v_cvt_pk_bf16_f32 v2, v2, v3
	v_cvt_pk_bf16_f32 v3, v4, v5
	global_store_dwordx2 v[16:17], v[2:3], off offset:32
	global_load_dwordx4 v[2:5], v[150:151], off offset:352
	v_mul_f32_e32 v25, v46, v24
	v_mul_f32_e32 v26, v47, v24
	v_mul_f32_e32 v27, v48, v24
	v_mul_f32_e32 v28, v49, v24
	s_waitcnt vmcnt(0)
	v_mul_f32_e32 v2, v2, v25
	v_mul_f32_e32 v3, v3, v26
	v_mul_f32_e32 v4, v4, v27
	v_mul_f32_e32 v5, v5, v28
	v_cvt_pk_bf16_f32 v2, v2, v3
	v_cvt_pk_bf16_f32 v3, v4, v5
	global_store_dwordx2 v[16:17], v[2:3], off offset:48
	global_load_dwordx4 v[2:5], v[150:151], off offset:384
	s_waitcnt vmcnt(0)
	v_mul_f32_e32 v2, v2, v18
	v_mul_f32_e32 v3, v3, v19
	v_mul_f32_e32 v4, v4, v20
	v_mul_f32_e32 v5, v5, v21
	v_cvt_pk_bf16_f32 v2, v2, v3
	v_cvt_pk_bf16_f32 v3, v4, v5
	global_store_dwordx2 v[16:17], v[2:3], off offset:64
	global_load_dwordx4 v[2:5], v[150:151], off offset:416
	v_mul_f32_e32 v18, v22, v24
	v_mul_f32_e32 v19, v23, v24
	s_waitcnt vmcnt(0)
	v_mul_f32_e32 v2, v2, v18
	v_mul_f32_e32 v3, v3, v19
	v_mul_f32_e32 v4, v4, v6
	v_mul_f32_e32 v5, v5, v7
	v_cvt_pk_bf16_f32 v2, v2, v3
	v_cvt_pk_bf16_f32 v3, v4, v5
	global_store_dwordx2 v[16:17], v[2:3], off offset:80
	global_load_dwordx4 v[2:5], v[150:151], off offset:448
	v_mul_f32_e32 v6, v8, v24
	v_mul_f32_e32 v7, v9, v24
	v_mul_f32_e32 v8, v10, v24
	v_mul_f32_e32 v9, v11, v24
	s_waitcnt vmcnt(0)
	v_mul_f32_e32 v2, v6, v2
	v_mul_f32_e32 v3, v7, v3
	v_mul_f32_e32 v4, v8, v4
	v_mul_f32_e32 v5, v9, v5
	v_cvt_pk_bf16_f32 v2, v2, v3
	v_cvt_pk_bf16_f32 v3, v4, v5
	global_store_dwordx2 v[16:17], v[2:3], off offset:96
	global_load_dwordx4 v[2:5], v[150:151], off offset:480
	v_mul_f32_e32 v6, v12, v24
	v_mul_f32_e32 v7, v13, v24
	v_mul_f32_e32 v8, v14, v24
	v_mul_f32_e32 v9, v15, v24
	s_waitcnt vmcnt(0)
	v_mul_f32_e32 v2, v6, v2
	v_mul_f32_e32 v3, v7, v3
	v_mul_f32_e32 v4, v8, v4
	v_mul_f32_e32 v5, v9, v5
	v_cvt_pk_bf16_f32 v2, v2, v3
	v_cvt_pk_bf16_f32 v3, v4, v5
	global_store_dwordx2 v[16:17], v[2:3], off offset:112
	s_cbranch_scc0 .LBB0_1437
	s_or_b32 s14, s0, 16
	s_ashr_i32 s15, s14, 31
	s_and_b32 s16, 0xffff, s1
	s_lshl_b64 s[14:15], s[14:15], 23
	s_add_u32 s12, s54, s14
	s_addc_u32 s14, s55, s15
	s_lshl_b32 s15, s16, 14
	s_add_u32 s15, s12, s15
	s_addc_u32 s17, s14, 0
	s_lshl_b32 s12, s16, 6
	s_and_b32 s12, s12, 0x3c0
	s_lshl_b32 s14, s12, 2
	s_add_u32 s14, s15, s14
	s_addc_u32 s15, s17, 0
	s_lshl_b32 s17, s0, 22
	s_add_u32 s17, s25, s17
	s_addc_u32 s18, s26, 0
	s_lshl_b32 s16, s16, 13
	s_add_u32 s16, s17, s16
	s_addc_u32 s17, s18, 0
	s_mov_b64 s[20:21], 0
	s_mov_b64 s[18:19], s[12:13]
